# attention MoBA/SWA loops: drop vmcnt from QK-phase waits (next-tile loads no longer drained at step start); vmcnt(0) once before loop
# baseline (speedup 1.0000x reference)
; template <int DQ, int TYPE>
; __device__ __forceinline__ void attn_item(PP p, int layer, int b, int h, int qt, char* lds, const int tid_, unsigned* next_ctr, volatile XLAS unsigned* slot) {
;     ...
;     f32x16 O[4];
; #pragma unroll
;     for (int md = 0; md < 4; ++md)
; #pragma unroll
;         for (int i = 0; i < 16; ++i) O[md][i] = 0.f;
;     float m_run = -1e30f, l_run = 0.f;
;     if (TYPE == 2 && kh == 0) { m_run = p->sinks[layer * 8 + h] * LOG2E; l_run = (hh == 0) ? 1.f : 0.f; }
;     constexpr int GK = (DQ == 192) ? 3 : 4, NG = NKS / GK;
;     A_LSTORE(A, 0); __syncthreads();
;     if (kh == 0) __builtin_amdgcn_s_setprio(2);
; #pragma unroll 1
;     for (int j = j_lo; j <= j_hi; ++j) {
;         const int buf = (j - j_lo) & 1;
;         if (j < j_hi) A_GLOAD(A, j + 1);
;         int mode = 0;
;         if (TYPE == 2) mode = 2;
;         else if (TYPE == 1 && (j >> 2) < own) mode = 3;
;         else if (j >= 2 * qt) mode = 1;
;         const int kbase_pos = 64 * j + 32 * kh;
;         const int qlo = 128 * qt + 32 * qg;
;         bool skip = false;
;         if (mode == 1 || mode == 2) { if (kbase_pos > qlo + 31) skip = true; }
;         if (mode == 2) { if (kbase_pos + 31 <= qlo - 128) skip = true; }
.LBB0_402:
	s_or_b32 s13, s51, 1
	s_ashr_i32 s56, s16, 8
	s_cmp_gt_i32 s12, s13
	v_lshlrev_b32_e32 v155, 2, v3
	s_cbranch_scc1 .LBB0_413
	s_lshl_b32 s13, s56, 5
	v_or_b32_e32 v0, s13, v2
	s_add_i32 s16, s15, 0xf65
	v_mul_lo_u32 v163, v0, s84
	v_add_u32_e32 v0, s16, v2
	s_lshl_b32 s16, s12, 6
	s_add_i32 s59, s16, s13
	v_lshlrev_b32_e32 v16, 3, v3
	v_or_b32_e32 v3, s59, v155
	v_sub_u32_e32 v0, v0, v3
	s_lshl_b32 s14, s14, 7
	v_subrev_u32_e32 v165, s14, v0
	s_add_i32 s14, s14, s59
	s_addk_i32 s14, 0xf080
	v_or_b32_e32 v0, s14, v155
	v_sub_u32_e32 v0, v0, v2
	v_mov_b32_e32 v14, v1
	v_mov_b32_e32 v15, v1
	v_mul_u32_u24_e32 v164, 0x88, v2
	v_subrev_u32_e32 v166, s15, v0
	v_mov_b32_e32 v0, v1
	v_mov_b32_e32 v2, v1
	v_mov_b32_e32 v3, v1
	v_mov_b32_e32 v4, v1
	v_mov_b32_e32 v5, v1
	v_mov_b32_e32 v6, v1
	v_mov_b32_e32 v7, v1
	v_mov_b32_e32 v8, v1
	v_mov_b32_e32 v9, v1
	v_mov_b32_e32 v10, v1
	v_mov_b32_e32 v11, v1
	v_mov_b32_e32 v12, v1
	v_mov_b32_e32 v13, v1
	v_lshlrev_b32_e32 v167, 1, v16
	v_mov_b64_e32 v[46:47], v[14:15]
	v_mov_b64_e32 v[30:31], v[14:15]
	v_mov_b64_e32 v[78:79], v[14:15]
	v_mov_b64_e32 v[62:63], v[14:15]
	v_mul_u32_u24_e32 v162, 0x88, v157
	s_or_b32 s57, s58, 31
	s_addk_i32 s58, 0xff80
	v_mov_b64_e32 v[44:45], v[12:13]
	v_mov_b64_e32 v[42:43], v[10:11]
	v_mov_b64_e32 v[40:41], v[8:9]
	v_mov_b64_e32 v[38:39], v[6:7]
	v_mov_b64_e32 v[36:37], v[4:5]
	v_mov_b64_e32 v[34:35], v[2:3]
	v_mov_b64_e32 v[32:33], v[0:1]
	v_mov_b64_e32 v[28:29], v[12:13]
	v_mov_b64_e32 v[26:27], v[10:11]
	v_mov_b64_e32 v[24:25], v[8:9]
	v_mov_b64_e32 v[22:23], v[6:7]
	v_mov_b64_e32 v[20:21], v[4:5]
	v_mov_b64_e32 v[18:19], v[2:3]
	v_mov_b64_e32 v[16:17], v[0:1]
	v_mov_b64_e32 v[76:77], v[12:13]
	v_mov_b64_e32 v[74:75], v[10:11]
	v_mov_b64_e32 v[72:73], v[8:9]
	v_mov_b64_e32 v[70:71], v[6:7]
	v_mov_b64_e32 v[68:69], v[4:5]
	v_mov_b64_e32 v[66:67], v[2:3]
	v_mov_b64_e32 v[64:65], v[0:1]
	v_mov_b64_e32 v[60:61], v[12:13]
	v_mov_b64_e32 v[58:59], v[10:11]
	v_mov_b64_e32 v[56:57], v[8:9]
	v_mov_b64_e32 v[54:55], v[6:7]
	v_mov_b64_e32 v[52:53], v[4:5]
	v_mov_b64_e32 v[50:51], v[2:3]
	v_mov_b64_e32 v[48:49], v[0:1]
	s_waitcnt vmcnt(0)
	s_branch .LBB0_406

; template <int DQ, int TYPE>
; __device__ __forceinline__ void attn_item(PP p, int layer, int b, int h, int qt, char* lds, const int tid_, unsigned* next_ctr, volatile XLAS unsigned* slot) {
;     ...
;         if (!skip) {
;             const bf16_t* Ks = (const bf16_t*)(lds + buf * STAGE); const bf16_t* Vt = (const bf16_t*)(lds + buf * STAGE + KBYTES);
;             f32x16 sacc;
; #pragma unroll
;             for (int i = 0; i < 16; ++i) sacc[i] = 0.f;
;             const bf16_t* kb_ = Ks + (32 * kh + r) * KLD + 8 * hh;
;             bf16x8 kf[2][GK];
; #pragma unroll
;             for (int i = 0; i < GK; ++i) kf[0][i] = *(const bf16x8*)(kb_ + 16 * i);
; #pragma unroll
;             for (int g = 0; g < NG; ++g) {
;                 if (g + 1 < NG) {
; #pragma unroll
;                     for (int i = 0; i < GK; ++i) kf[(g + 1) & 1][i] = *(const bf16x8*)(kb_ + 16 * ((g + 1) * GK + i));
;                 }
;                 __builtin_amdgcn_sched_barrier(0);
; #pragma unroll
;                 for (int i = 0; i < GK; ++i) sacc = __builtin_amdgcn_mfma_f32_32x32x16_bf16(kf[g & 1][i], qf[g * GK + i], sacc, 0, 0, 0);
;                 __builtin_amdgcn_sched_barrier(0);
;             }
;             const bf16_t* vb0 = Vt + r * VLD + 32 * kh + 4 * hh;
;             u32x2 vf[2][4][2];
; #pragma unroll
;             for (int md = 0; md < 4; ++md) { vf[0][md][0] = *(const u32x2*)(vb0 + md * 32 * VLD); vf[0][md][1] = *(const u32x2*)(vb0 + md * 32 * VLD + 8); }
;             if (mode != 0) {
;                 const bool selbit = (qmask >> (j >> 2)) & 1u;
; #pragma unroll
;                 for (int i = 0; i < 16; ++i) {
;                     const int kpos = kbase_pos + 8 * (i >> 2) + 4 * hh + (i & 3);
;                     const int dd = qpos - kpos;
;                     bool ok;
;                     if (mode == 1) ok = dd >= 0; else if (mode == 2) ok = (dd >= 0 && dd < 128); else ok = selbit;
;                     if (!ok) sacc[i] = -INFINITY;
;                 }
;             }
;             float mx = fmaxf(sacc[0], sacc[1]);
; #pragma unroll
;             for (int i = 2; i < 16; i += 2) mx = fmaxf(mx, fmaxf(sacc[i], sacc[i + 1]));
;             mx *= c;
;             mx = fmaxf(mx, __shfl_xor(mx, 32));
;             const float m_old_ = m_run;
;             const float mnew = fmaxf(m_run, mx);
;             const float alpha = fast_exp2(m_run - mnew);
.LBB0_408:
	s_and_b32 s60, s12, 1
	s_cmp_gt_i32 s59, s57
	s_cselect_b64 s[62:63], -1, 0
	s_add_i32 s61, s59, 31
	s_cmp_le_i32 s61, s58
	s_cselect_b64 s[64:65], -1, 0
	s_or_b64 s[62:63], s[64:65], s[62:63]
	s_and_b64 vcc, exec, s[62:63]
	s_cbranch_vccnz .LBB0_412
	s_mul_i32 s61, s60, 0x8800
	s_add_i32 s61, s61, 16
	v_add3_u32 v0, s61, v163, v167
	ds_read_b128 v[2:5], v0
	ds_read_b128 v[6:9], v0 offset:32
	ds_read_b128 v[10:13], v0 offset:64
	ds_read_b128 v[170:173], v0 offset:96
	ds_read_b128 v[174:177], v0 offset:128
	ds_read_b128 v[190:193], v0 offset:160
	ds_read_b128 v[194:197], v0 offset:192
	ds_read_b128 v[198:201], v0 offset:224
	s_waitcnt lgkmcnt(7)
	v_mfma_f32_32x32x16_bf16 v[80:95], v[2:5], v[104:107], 0
	s_waitcnt lgkmcnt(6)
	v_mfma_f32_32x32x16_bf16 v[80:95], v[6:9], v[108:111], v[80:95]
	s_waitcnt lgkmcnt(5)
	v_mfma_f32_32x32x16_bf16 v[80:95], v[10:13], v[112:115], v[80:95]
	s_waitcnt lgkmcnt(4)
	v_mfma_f32_32x32x16_bf16 v[80:95], v[170:173], v[120:123], v[80:95]
	s_waitcnt lgkmcnt(3)
	v_mfma_f32_32x32x16_bf16 v[80:95], v[174:177], v[124:127], v[80:95]
	s_lshl_b32 s62, s13, 1
	v_add_u32_e32 v10, 27, v165
	s_add_i32 s62, s62, s61
	v_cmp_gt_u32_e32 vcc, s42, v10
	s_movk_i32 s61, 0xff7f
	v_add_u32_e32 v11, 25, v165
	v_add_u32_e32 v12, 24, v165
	s_waitcnt lgkmcnt(2)
	v_mfma_f32_32x32x16_bf16 v[80:95], v[190:193], v[132:135], v[80:95]
	v_add_u32_e32 v13, 19, v165
	v_add_u32_e32 v14, 18, v165
	v_add_u32_e32 v175, 17, v165
	v_add_u32_e32 v176, 16, v165
	v_add_u32_e32 v10, 11, v165
	v_lshlrev_b32_e32 v0, 1, v155
	v_add3_u32 v0, s62, v164, v0
	s_waitcnt lgkmcnt(1)
	v_mfma_f32_32x32x16_bf16 v[80:95], v[194:197], v[136:139], v[80:95]
	v_add_u32_e32 v169, 0x4000, v0
	v_add_u32_e32 v15, 0x5000, v0
	ds_read2_b64 v[2:5], v169 offset0:128 offset1:130
	ds_read2_b64 v[6:9], v15 offset0:160 offset1:162
	s_waitcnt lgkmcnt(2)
	v_mfma_f32_32x32x16_bf16 v[80:95], v[198:201], v[140:143], v[80:95]
	s_nop 11
	v_cndmask_b32_e32 v170, v225, v80, vcc
	v_cmp_lt_u32_e32 vcc, s61, v166
	s_nop 1
	v_cndmask_b32_e32 v172, v225, v81, vcc
	v_cmp_gt_u32_e32 vcc, s42, v11
	s_nop 1
	v_cndmask_b32_e32 v173, v225, v82, vcc
	v_cmp_gt_u32_e32 vcc, s42, v12
	v_max_f32_e32 v11, v173, v173
	s_nop 0
	v_cndmask_b32_e32 v174, v225, v83, vcc
	v_cmp_gt_u32_e32 vcc, s42, v13
	s_nop 1
	v_cndmask_b32_e32 v171, v225, v84, vcc
	v_cmp_gt_u32_e32 vcc, s42, v14
	v_max_f32_e32 v12, v171, v171
	s_nop 0
	v_cndmask_b32_e32 v85, v225, v85, vcc
	v_cmp_gt_u32_e32 vcc, s42, v175
	s_nop 1
	v_cndmask_b32_e32 v177, v225, v86, vcc
	v_cmp_gt_u32_e32 vcc, s42, v176
	v_max_f32_e32 v13, v177, v177
	s_nop 0
	v_cndmask_b32_e32 v176, v225, v87, vcc
	v_cmp_gt_u32_e32 vcc, s42, v10
	v_add_u32_e32 v10, 10, v165
	s_nop 0
	v_cndmask_b32_e32 v175, v225, v88, vcc
	v_cmp_gt_u32_e32 vcc, s42, v10
	v_add_u32_e32 v10, 9, v165
	s_nop 0
	v_cndmask_b32_e32 v89, v225, v89, vcc
	v_cmp_gt_u32_e32 vcc, s42, v10
	v_add_u32_e32 v10, 8, v165
	s_nop 0
	v_cndmask_b32_e32 v90, v225, v90, vcc
	v_cmp_gt_u32_e32 vcc, s42, v10
	v_add_u32_e32 v10, 3, v165
	s_nop 0
	v_cndmask_b32_e32 v91, v225, v91, vcc
	v_cmp_gt_u32_e32 vcc, s42, v10
	v_add_u32_e32 v10, 2, v165
	s_nop 0
	v_cndmask_b32_e32 v86, v225, v92, vcc
	v_cmp_gt_u32_e32 vcc, s42, v10
	v_add_u32_e32 v10, 1, v165
	v_add_u32_e32 v92, 0x7000, v0
	v_cndmask_b32_e32 v87, v225, v93, vcc
	v_cmp_gt_u32_e32 vcc, s42, v10
	v_max_f32_e32 v10, v174, v174
	v_max_f32_e32 v10, v11, v10
	v_max_f32_e32 v11, v85, v85
	v_max_f32_e32 v11, v12, v11
	v_max_f32_e32 v12, v176, v176
	v_max3_f32 v10, v170, v172, v10
	v_max_f32_e32 v12, v13, v12
	v_max3_f32 v10, v10, v11, v12
	v_max_f32_e32 v11, v89, v89
	v_max_f32_e32 v12, v175, v175
	v_max_f32_e32 v11, v12, v11
	v_max_f32_e32 v12, v91, v91
	v_max_f32_e32 v13, v90, v90
	v_cndmask_b32_e32 v88, v225, v94, vcc
	v_cmp_gt_u32_e32 vcc, s42, v165
	v_max_f32_e32 v12, v13, v12
	v_max3_f32 v10, v10, v11, v12
	v_cndmask_b32_e32 v84, v225, v95, vcc
	v_max_f32_e32 v11, v87, v87
	v_max_f32_e32 v12, v86, v86
	v_max_f32_e32 v11, v12, v11
	v_max_f32_e32 v12, v84, v84
	v_max_f32_e32 v13, v88, v88
	v_max_f32_e32 v12, v13, v12
	v_max3_f32 v10, v10, v11, v12
	v_and_b32_e32 v11, 64, v224
	v_mul_f32_e32 v14, 0x3e0293ee, v10
	v_xor_b32_e32 v10, 32, v224
	v_add_u32_e32 v11, 64, v11
	v_cmp_lt_i32_e32 vcc, v10, v11
	v_add_u32_e32 v93, 0x6000, v0
	ds_read2_b64 v[80:83], v93 offset0:192 offset1:194
	v_cndmask_b32_e32 v10, v224, v10, vcc
	v_lshlrev_b32_e32 v10, 2, v10
	ds_bpermute_b32 v94, v10, v14
	ds_read2_b64 v[10:13], v92 offset0:224 offset1:226
	s_waitcnt lgkmcnt(1)
	v_max_f32_e32 v0, v94, v94
	v_max_f32_e32 v94, v14, v0
	v_max_f32_e32 v0, v168, v168
	v_max_f32_e32 v14, v0, v94
	v_sub_f32_e32 v0, v168, v14
	v_exp_f32_e32 v0, v0
	v_cmp_gt_f32_e32 vcc, v94, v168
	s_cbranch_vccz .LBB0_411
	v_pk_mul_f32 v[46:47], v[46:47], v[0:1] op_sel_hi:[1,0]
	v_pk_mul_f32 v[44:45], v[44:45], v[0:1] op_sel_hi:[1,0]
	v_pk_mul_f32 v[42:43], v[42:43], v[0:1] op_sel_hi:[1,0]
	v_pk_mul_f32 v[40:41], v[40:41], v[0:1] op_sel_hi:[1,0]
	v_pk_mul_f32 v[38:39], v[38:39], v[0:1] op_sel_hi:[1,0]
	v_pk_mul_f32 v[36:37], v[36:37], v[0:1] op_sel_hi:[1,0]
	v_pk_mul_f32 v[34:35], v[34:35], v[0:1] op_sel_hi:[1,0]
	v_pk_mul_f32 v[32:33], v[32:33], v[0:1] op_sel_hi:[1,0]
	v_pk_mul_f32 v[30:31], v[30:31], v[0:1] op_sel_hi:[1,0]
	v_pk_mul_f32 v[28:29], v[28:29], v[0:1] op_sel_hi:[1,0]
	v_pk_mul_f32 v[26:27], v[26:27], v[0:1] op_sel_hi:[1,0]
	v_pk_mul_f32 v[24:25], v[24:25], v[0:1] op_sel_hi:[1,0]
	v_pk_mul_f32 v[22:23], v[22:23], v[0:1] op_sel_hi:[1,0]
	v_pk_mul_f32 v[20:21], v[20:21], v[0:1] op_sel_hi:[1,0]
	v_pk_mul_f32 v[18:19], v[18:19], v[0:1] op_sel_hi:[1,0]
	v_pk_mul_f32 v[16:17], v[16:17], v[0:1] op_sel_hi:[1,0]
	v_pk_mul_f32 v[78:79], v[78:79], v[0:1] op_sel_hi:[1,0]
	v_pk_mul_f32 v[76:77], v[76:77], v[0:1] op_sel_hi:[1,0]
	v_pk_mul_f32 v[74:75], v[74:75], v[0:1] op_sel_hi:[1,0]
	v_pk_mul_f32 v[72:73], v[72:73], v[0:1] op_sel_hi:[1,0]
	v_pk_mul_f32 v[70:71], v[70:71], v[0:1] op_sel_hi:[1,0]
	v_pk_mul_f32 v[68:69], v[68:69], v[0:1] op_sel_hi:[1,0]
	v_pk_mul_f32 v[66:67], v[66:67], v[0:1] op_sel_hi:[1,0]
	v_pk_mul_f32 v[64:65], v[64:65], v[0:1] op_sel_hi:[1,0]
	v_pk_mul_f32 v[62:63], v[62:63], v[0:1] op_sel_hi:[1,0]
	v_pk_mul_f32 v[60:61], v[60:61], v[0:1] op_sel_hi:[1,0]
	v_pk_mul_f32 v[58:59], v[58:59], v[0:1] op_sel_hi:[1,0]
	v_pk_mul_f32 v[56:57], v[56:57], v[0:1] op_sel_hi:[1,0]
	v_pk_mul_f32 v[54:55], v[54:55], v[0:1] op_sel_hi:[1,0]
	v_pk_mul_f32 v[52:53], v[52:53], v[0:1] op_sel_hi:[1,0]
	v_pk_mul_f32 v[50:51], v[50:51], v[0:1] op_sel_hi:[1,0]
	v_pk_mul_f32 v[48:49], v[48:49], v[0:1] op_sel_hi:[1,0]

; template <int DQ, int TYPE>
; __device__ __forceinline__ void attn_item(PP p, int layer, int b, int h, int qt, char* lds, const int tid_, unsigned* next_ctr, volatile XLAS unsigned* slot) {
;     ...
;     f32x16 O[4];
; #pragma unroll
;     for (int md = 0; md < 4; ++md)
; #pragma unroll
;         for (int i = 0; i < 16; ++i) O[md][i] = 0.f;
;     float m_run = -1e30f, l_run = 0.f;
;     if (TYPE == 2 && kh == 0) { m_run = p->sinks[layer * 8 + h] * LOG2E; l_run = (hh == 0) ? 1.f : 0.f; }
;     constexpr int GK = (DQ == 192) ? 3 : 4, NG = NKS / GK;
;     A_LSTORE(A, 0); __syncthreads();
;     if (kh == 0) __builtin_amdgcn_s_setprio(2);
; #pragma unroll 1
;     for (int j = j_lo; j <= j_hi; ++j) {
;         const int buf = (j - j_lo) & 1;
;         if (j < j_hi) A_GLOAD(A, j + 1);
;         int mode = 0;
;         if (TYPE == 2) mode = 2;
;         else if (TYPE == 1 && (j >> 2) < own) mode = 3;
;         else if (j >= 2 * qt) mode = 1;
;         const int kbase_pos = 64 * j + 32 * kh;
;         const int qlo = 128 * qt + 32 * qg;
;         bool skip = false;
;         if (mode == 1 || mode == 2) { if (kbase_pos > qlo + 31) skip = true; }
;         if (mode == 2) { if (kbase_pos + 31 <= qlo - 128) skip = true; }
.LBB0_637:
	s_waitcnt vmcnt(0)
	s_ashr_i32 s54, s88, 8
	s_lshl_b32 s58, s54, 5
	v_or_b32_e32 v2, s58, v154
	v_mov_b32_e32 v18, v1
	v_mov_b32_e32 v19, v1
	v_mov_b32_e32 v32, v1
	v_mov_b32_e32 v33, v1
	v_mul_lo_u32 v162, v2, s84
	s_lshl_b32 s12, s49, 1
	v_mov_b32_e32 v20, v1
	v_mov_b32_e32 v21, v1
	v_mov_b32_e32 v22, v1
	v_mov_b32_e32 v23, v1
	v_mov_b32_e32 v24, v1
	v_mov_b32_e32 v25, v1
	v_mov_b32_e32 v26, v1
	v_mov_b32_e32 v27, v1
	v_mov_b32_e32 v28, v1
	v_mov_b32_e32 v29, v1
	v_mov_b32_e32 v30, v1
	v_mov_b32_e32 v31, v1
	v_mov_b64_e32 v[2:3], v[18:19]
	v_mov_b64_e32 v[64:65], v[32:33]
	v_mov_b64_e32 v[48:49], v[32:33]
	v_mul_u32_u24_e32 v161, 0x88, v185
	s_lshl_b32 s57, s80, 1
	s_or_b32 s59, s95, 31
	v_mul_u32_u24_e32 v163, 0x88, v154
	v_lshlrev_b32_e32 v147, 2, v155
	s_sub_i32 s60, 64, s12
	s_mov_b32 s61, 0
	v_mov_b32_e32 v164, 0
	v_mov_b32_e32 v176, 0xf149f2ca
	s_mov_b32 s62, s58
	v_mov_b64_e32 v[4:5], v[20:21]
	v_mov_b64_e32 v[6:7], v[22:23]
	v_mov_b64_e32 v[8:9], v[24:25]
	v_mov_b64_e32 v[10:11], v[26:27]
	v_mov_b64_e32 v[12:13], v[28:29]
	v_mov_b64_e32 v[14:15], v[30:31]
	v_mov_b64_e32 v[16:17], v[32:33]
	v_mov_b64_e32 v[62:63], v[30:31]
	v_mov_b64_e32 v[60:61], v[28:29]
	v_mov_b64_e32 v[58:59], v[26:27]
	v_mov_b64_e32 v[56:57], v[24:25]
	v_mov_b64_e32 v[54:55], v[22:23]
	v_mov_b64_e32 v[52:53], v[20:21]
	v_mov_b64_e32 v[50:51], v[18:19]
	v_mov_b64_e32 v[46:47], v[30:31]
	v_mov_b64_e32 v[44:45], v[28:29]
	v_mov_b64_e32 v[42:43], v[26:27]
	v_mov_b64_e32 v[40:41], v[24:25]
	v_mov_b64_e32 v[38:39], v[22:23]
	v_mov_b64_e32 v[36:37], v[20:21]
	v_mov_b64_e32 v[34:35], v[18:19]
	s_cmp_le_u32 s61, s57
	s_cselect_b64 s[12:13], -1, 0
	s_cmp_gt_u32 s61, s57
	s_cbranch_scc1 .LBB0_640
	s_branch .LBB0_639

; template <int DQ, int TYPE>
; __device__ __forceinline__ void attn_item(PP p, int layer, int b, int h, int qt, char* lds, const int tid_, unsigned* next_ctr, volatile XLAS unsigned* slot) {
;     ...
;     for (int j = j_lo; j <= j_hi; ++j) {
;         const int buf = (j - j_lo) & 1;
;         if (j < j_hi) A_GLOAD(A, j + 1);
;         int mode = 0;
;         if (TYPE == 2) mode = 2;
;         else if (TYPE == 1 && (j >> 2) < own) mode = 3;
;         else if (j >= 2 * qt) mode = 1;
;         const int kbase_pos = 64 * j + 32 * kh;
;         const int qlo = 128 * qt + 32 * qg;
;         bool skip = false;
;         if (mode == 1 || mode == 2) { if (kbase_pos > qlo + 31) skip = true; }
;         if (mode == 2) { if (kbase_pos + 31 <= qlo - 128) skip = true; }
;         if (!skip) {
;             const bf16_t* Ks = (const bf16_t*)(lds + buf * STAGE); const bf16_t* Vt = (const bf16_t*)(lds + buf * STAGE + KBYTES);
;             f32x16 sacc;
; #pragma unroll
;             for (int i = 0; i < 16; ++i) sacc[i] = 0.f;
;             const bf16_t* kb_ = Ks + (32 * kh + r) * KLD + 8 * hh;
;             bf16x8 kf[2][GK];
; #pragma unroll
;             for (int i = 0; i < GK; ++i) kf[0][i] = *(const bf16x8*)(kb_ + 16 * i);
; #pragma unroll
;             for (int g = 0; g < NG; ++g) {
;                 if (g + 1 < NG) {
; #pragma unroll
;                     for (int i = 0; i < GK; ++i) kf[(g + 1) & 1][i] = *(const bf16x8*)(kb_ + 16 * ((g + 1) * GK + i));
;                 }
;                 __builtin_amdgcn_sched_barrier(0);
; #pragma unroll
;                 for (int i = 0; i < GK; ++i) sacc = __builtin_amdgcn_mfma_f32_32x32x16_bf16(kf[g & 1][i], qf[g * GK + i], sacc, 0, 0, 0);
;                 __builtin_amdgcn_sched_barrier(0);
;             }
;             const bf16_t* vb0 = Vt + r * VLD + 32 * kh + 4 * hh;
;             u32x2 vf[2][4][2];
; #pragma unroll
;             for (int md = 0; md < 4; ++md) { vf[0][md][0] = *(const u32x2*)(vb0 + md * 32 * VLD); vf[0][md][1] = *(const u32x2*)(vb0 + md * 32 * VLD + 8); }
;             if (mode != 0) {
;                 const bool selbit = (qmask >> (j >> 2)) & 1u;
; #pragma unroll
;                 for (int i = 0; i < 16; ++i) {
;                     const int kpos = kbase_pos + 8 * (i >> 2) + 4 * hh + (i & 3);
;                     const int dd = qpos - kpos;
;                     bool ok;
.LBB0_640:
	s_and_b32 s63, s61, 1
	s_lshr_b32 s64, s61, 2
	s_cmp_ge_u32 s64, s94
	s_cselect_b64 s[14:15], -1, 0
	s_cmp_lt_u32 s61, s57
	s_cselect_b64 s[16:17], -1, 0
	s_cmp_ge_u32 s61, s57
	s_cselect_b64 s[50:51], -1, 0
	s_and_b64 s[50:51], s[14:15], s[50:51]
	s_cmp_gt_i32 s62, s59
	s_cselect_b64 s[66:67], -1, 0
	s_and_b64 s[66:67], s[50:51], s[66:67]
	s_and_b64 vcc, exec, s[66:67]
	s_cbranch_vccnz .LBB0_646
	s_and_b64 s[14:15], s[14:15], s[16:17]
	s_mul_i32 s16, s63, 0x8800
	s_add_i32 s16, s16, 16
	v_lshlrev_b32_e32 v66, 1, v153
	v_add3_u32 v70, s16, v162, v66
	ds_read_b128 v[66:69], v70
	ds_read_b128 v[130:133], v70 offset:32
	ds_read_b128 v[134:137], v70 offset:64
	ds_read_b128 v[138:141], v70 offset:96
	ds_read_b128 v[142:145], v70 offset:128
	ds_read_b128 v[172:175], v70 offset:160
	ds_read_b128 v[190:193], v70 offset:192
	ds_read_b128 v[194:197], v70 offset:224
	s_waitcnt lgkmcnt(7)
	v_mfma_f32_32x32x16_bf16 v[66:81], v[66:69], v[90:93], 0
	s_waitcnt lgkmcnt(6)
	v_mfma_f32_32x32x16_bf16 v[66:81], v[130:133], v[94:97], v[66:81]
	s_waitcnt lgkmcnt(5)
	v_mfma_f32_32x32x16_bf16 v[66:81], v[134:137], v[98:101], v[66:81]
	s_waitcnt lgkmcnt(4)
	v_mfma_f32_32x32x16_bf16 v[66:81], v[138:141], v[102:105], v[66:81]
	s_waitcnt lgkmcnt(3)
	v_mfma_f32_32x32x16_bf16 v[66:81], v[142:145], v[110:113], v[66:81]
	s_lshl_b32 s17, s58, 1
	s_add_i32 s17, s17, s16
	v_lshlrev_b32_e32 v130, 1, v147
	v_add3_u32 v130, s17, v163, v130
	s_and_b64 vcc, exec, s[14:15]
	s_waitcnt lgkmcnt(2)
	v_mfma_f32_32x32x16_bf16 v[66:81], v[172:175], v[114:117], v[66:81]
	v_add_u32_e32 v173, 0x4000, v130
	v_add_u32_e32 v175, 0x5000, v130
	v_add_u32_e32 v174, 0x6000, v130
	v_add_u32_e32 v172, 0x7000, v130
	ds_read2_b64 v[142:145], v173 offset0:128 offset1:130
	ds_read2_b64 v[138:141], v175 offset0:160 offset1:162
	ds_read2_b64 v[134:137], v174 offset0:192 offset1:194
	s_waitcnt lgkmcnt(4)
	v_mfma_f32_32x32x16_bf16 v[66:81], v[190:193], v[122:125], v[66:81]
	ds_read2_b64 v[130:133], v172 offset0:224 offset1:226
	s_waitcnt lgkmcnt(4)
	v_mfma_f32_32x32x16_bf16 v[66:81], v[194:197], v[126:129], v[66:81]
	s_cbranch_vccnz .LBB0_643
	v_add_u32_e32 v165, s62, v147
	v_cmp_ge_i32_e32 vcc, v0, v165
	v_lshrrev_b32_e32 v152, s64, v157
	s_nop 0
	v_cndmask_b32_e64 v177, 0, 1, vcc
	v_cndmask_b32_e64 v177, v152, v177, s[50:51]
	v_and_b32_e32 v177, 1, v177
	v_cmp_eq_u32_e32 vcc, 1, v177
	s_nop 2
	v_cndmask_b32_e32 v66, v225, v66, vcc
	v_cmp_gt_i32_e32 vcc, v0, v165
	s_nop 1
	v_cndmask_b32_e64 v177, 0, 1, vcc
	v_cndmask_b32_e64 v177, v152, v177, s[50:51]
	v_and_b32_e32 v177, 1, v177
	v_cmp_eq_u32_e32 vcc, 1, v177
	v_add_u32_e32 v177, 2, v165
	s_nop 0
	v_cndmask_b32_e32 v67, v225, v67, vcc
	v_cmp_ge_i32_e32 vcc, v0, v177
	s_nop 1
	v_cndmask_b32_e64 v177, 0, 1, vcc
	v_cndmask_b32_e64 v177, v152, v177, s[50:51]
	v_and_b32_e32 v177, 1, v177
	v_cmp_eq_u32_e32 vcc, 1, v177
	v_add_u32_e32 v177, 3, v165
	s_nop 0
	v_cndmask_b32_e32 v68, v225, v68, vcc
	v_cmp_ge_i32_e32 vcc, v0, v177
	s_nop 1
	v_cndmask_b32_e64 v177, 0, 1, vcc
	v_cndmask_b32_e64 v177, v152, v177, s[50:51]
	v_and_b32_e32 v177, 1, v177
	v_cmp_eq_u32_e32 vcc, 1, v177
	v_add_u32_e32 v177, 8, v165
	s_nop 0
	v_cndmask_b32_e32 v69, v225, v69, vcc
	v_cmp_ge_i32_e32 vcc, v0, v177
	s_nop 1
	v_cndmask_b32_e64 v177, 0, 1, vcc
	v_cndmask_b32_e64 v177, v152, v177, s[50:51]
	v_and_b32_e32 v177, 1, v177
	v_cmp_eq_u32_e32 vcc, 1, v177
	v_add_u32_e32 v177, 9, v165
	s_nop 0
	v_cndmask_b32_e32 v70, v225, v70, vcc
	v_cmp_ge_i32_e32 vcc, v0, v177
	s_nop 1
	v_cndmask_b32_e64 v177, 0, 1, vcc
	v_cndmask_b32_e64 v177, v152, v177, s[50:51]
	v_and_b32_e32 v177, 1, v177
	v_cmp_eq_u32_e32 vcc, 1, v177
	v_add_u32_e32 v177, 10, v165
	s_nop 0
	v_cndmask_b32_e32 v71, v225, v71, vcc
	v_cmp_ge_i32_e32 vcc, v0, v177
	s_nop 1
	v_cndmask_b32_e64 v177, 0, 1, vcc
	v_cndmask_b32_e64 v177, v152, v177, s[50:51]
	v_and_b32_e32 v177, 1, v177
	v_cmp_eq_u32_e32 vcc, 1, v177
	v_add_u32_e32 v177, 11, v165
	s_nop 0
	v_cndmask_b32_e32 v72, v225, v72, vcc
	v_cmp_ge_i32_e32 vcc, v0, v177
	s_nop 1
	v_cndmask_b32_e64 v177, 0, 1, vcc
	v_cndmask_b32_e64 v177, v152, v177, s[50:51]
	v_and_b32_e32 v177, 1, v177
	v_cmp_eq_u32_e32 vcc, 1, v177
	v_add_u32_e32 v177, 16, v165
	s_nop 0
	v_cndmask_b32_e32 v73, v225, v73, vcc
	v_cmp_ge_i32_e32 vcc, v0, v177
	s_nop 1
	v_cndmask_b32_e64 v177, 0, 1, vcc
	v_cndmask_b32_e64 v177, v152, v177, s[50:51]
	v_and_b32_e32 v177, 1, v177
	v_cmp_eq_u32_e32 vcc, 1, v177
	v_add_u32_e32 v177, 17, v165
	s_nop 0
	v_cndmask_b32_e32 v74, v225, v74, vcc
	v_cmp_ge_i32_e32 vcc, v0, v177
	s_nop 1
	v_cndmask_b32_e64 v177, 0, 1, vcc
	v_cndmask_b32_e64 v177, v152, v177, s[50:51]
	v_and_b32_e32 v177, 1, v177
	v_cmp_eq_u32_e32 vcc, 1, v177
	v_add_u32_e32 v177, 18, v165
	s_nop 0
	v_cndmask_b32_e32 v75, v225, v75, vcc
	v_cmp_ge_i32_e32 vcc, v0, v177
	s_nop 1
	v_cndmask_b32_e64 v177, 0, 1, vcc
	v_cndmask_b32_e64 v177, v152, v177, s[50:51]
	v_and_b32_e32 v177, 1, v177
	v_cmp_eq_u32_e32 vcc, 1, v177
	v_add_u32_e32 v177, 19, v165
	s_nop 0
	v_cndmask_b32_e32 v76, v225, v76, vcc
	v_cmp_ge_i32_e32 vcc, v0, v177
	s_nop 1
	v_cndmask_b32_e64 v177, 0, 1, vcc
	v_cndmask_b32_e64 v177, v152, v177, s[50:51]
	v_and_b32_e32 v177, 1, v177
	v_cmp_eq_u32_e32 vcc, 1, v177
	v_add_u32_e32 v177, 24, v165
	s_nop 0
	v_cndmask_b32_e32 v77, v225, v77, vcc
	v_cmp_ge_i32_e32 vcc, v0, v177
	s_nop 1
	v_cndmask_b32_e64 v177, 0, 1, vcc
	v_cndmask_b32_e64 v177, v152, v177, s[50:51]
	v_and_b32_e32 v177, 1, v177
	v_cmp_eq_u32_e32 vcc, 1, v177
	v_add_u32_e32 v177, 25, v165
	s_nop 0
	v_cndmask_b32_e32 v78, v225, v78, vcc
	v_cmp_ge_i32_e32 vcc, v0, v177
	s_nop 1
	v_cndmask_b32_e64 v177, 0, 1, vcc
	v_cndmask_b32_e64 v177, v152, v177, s[50:51]
	v_and_b32_e32 v177, 1, v177
	v_cmp_eq_u32_e32 vcc, 1, v177
	v_add_u32_e32 v177, 26, v165
	v_add_u32_e32 v165, 27, v165
	v_cndmask_b32_e32 v79, v225, v79, vcc
	v_cmp_ge_i32_e32 vcc, v0, v177
	s_nop 1
	v_cndmask_b32_e64 v177, 0, 1, vcc
	v_cndmask_b32_e64 v177, v152, v177, s[50:51]
	v_and_b32_e32 v177, 1, v177
	v_cmp_eq_u32_e32 vcc, 1, v177
	s_nop 1
	v_cndmask_b32_e32 v80, v225, v80, vcc
	v_cmp_ge_i32_e32 vcc, v0, v165
	s_nop 1
	v_cndmask_b32_e64 v165, 0, 1, vcc
	v_cndmask_b32_e64 v152, v152, v165, s[50:51]
	v_and_b32_e32 v152, 1, v152
	v_cmp_eq_u32_e32 vcc, 1, v152
	s_nop 1
	v_cndmask_b32_e32 v81, v225, v81, vcc
